# GU and IN: first K-tile of each tile writes the accumulators with SrcC=0 instead of 64 v_mov zeroing per tile
# speedup vs baseline: 1.0034x; 1.0034x over previous
; #define LAS __attribute__((address_space(3)))
; #define BAR() { __builtin_amdgcn_sched_barrier(0); __builtin_amdgcn_s_barrier(); asm volatile("" ::: "memory"); __builtin_amdgcn_sched_barrier(0); }
; DI void gemm_stream2(const bf16_t* __restrict__ A, int lda, const bf16_t* __restrict__ Bt, int ldb, int K, int m0, int n0, ...
;     ...
;     for (int kt = 0; kt < nk; ++kt) {
;         const bool pf = (kt + 2 < nk) || has_next, more = (kt + 1 < nk) || has_next;
;         const bf16_t* pa = (kt + 2 < nk) ? ga + (kt + 2) * 64 : gan + (kt + 2 - nk) * 64;
;         const bf16_t* pb = (kt + 2 < nk) ? gb + (kt + 2) * 64 : gbn + (kt + 2 - nk) * 64;
;         const int plda = (kt + 2 < nk) ? lda : ldan, pldb = (kt + 2 < nk) ? ldb : ldbn;
;         const int s2 = st >= 1 ? st - 1 : 2;
;         const LAS char* base = lds + st * 49152;
; #pragma unroll
;         for (int ks = 0; ks < 2; ++ks) {
;             const unsigned fo = ks ? fo1 : fo0;
;             bf16x8 af[4], bfr[4];
; #pragma unroll
;             for (int i = 0; i < 4; ++i) { af[i] = *(const LAS bf16x8*)(base + aoff + i * 2048 + fo); bfr[i] = *(const LAS bf16x8*)(base + boff + i * 2048 + fo); }
;             if (ks == 1 && more) { if (pf) asm volatile("s_waitcnt vmcnt(3)" ::: "memory"); else asm volatile("s_waitcnt vmcnt(0)" ::: "memory"); }
;             if (pf) { PIECE(s2, ks * 3 + 0); PIECE(s2, ks * 3 + 1); PIECE(s2, ks * 3 + 2); }
;             asm volatile("s_waitcnt lgkmcnt(0)" ::: "memory");
;             BAR();
;             __builtin_amdgcn_s_setprio(1);
; #pragma unroll
;             for (int mi = 0; mi < 4; ++mi)
; #pragma unroll
;                 for (int ni = 0; ni < 4; ++ni) acc[mi][ni] = __builtin_amdgcn_mfma_f32_16x16x32_bf16(bfr[ni], af[mi], acc[mi][ni], 0, 0, 0);
;             __builtin_amdgcn_s_setprio(0);
;             BAR();
;         }
; DI void zero_acc(f32x4 (&acc)[4][4]) {
; #pragma unroll
;     for (int i = 0; i < 4; ++i)
; #pragma unroll
;         for (int j = 0; j < 4; ++j) acc[i][j] = (f32x4){0.f, 0.f, 0.f, 0.f};
; }
.Lgu_nonext:
	s_add_u32 s0, s54, 7
	ds_read_b128 v[0:3], v188 offset:16
	ds_read_b128 v[4:7], v189 offset:16
	ds_read_b128 v[8:11], v188 offset:2064
	ds_read_b128 v[12:15], v189 offset:2064
	ds_read_b128 v[196:199], v188 offset:16400
	ds_read_b128 v[200:203], v189 offset:16400
	ds_read_b128 v[204:207], v188 offset:18448
	ds_read_b128 v[208:211], v189 offset:18448
	ds_read_b128 v[152:155], v186 offset:16
	ds_read_b128 v[156:159], v187 offset:16
	ds_read_b128 v[160:163], v186 offset:2064
	ds_read_b128 v[164:167], v187 offset:2064
	ds_read_b128 v[168:171], v186 offset:4112
	ds_read_b128 v[172:175], v187 offset:4112
	ds_read_b128 v[176:179], v186 offset:6160
	ds_read_b128 v[180:183], v187 offset:6160
	s_add_i32 m0, s39, 0xc000
	s_nop 0
	global_load_lds_dwordx4 v184, s[68:69]
	s_add_i32 m0, s39, 0xc400
	s_nop 0
	global_load_lds_dwordx4 v185, s[68:69]
	s_add_u32 s68, s68, 0x80
	s_addc_u32 s69, s69, 0
	s_waitcnt lgkmcnt(0)
	s_waitcnt vmcnt(8)
	s_barrier
	s_setprio 1
	v_mfma_f32_16x16x32_bf16 v[24:27], v[0:3], v[152:155], 0
	v_mfma_f32_16x16x32_bf16 v[28:31], v[8:11], v[152:155], 0
	v_mfma_f32_16x16x32_bf16 v[32:35], v[0:3], v[160:163], 0
	v_mfma_f32_16x16x32_bf16 v[36:39], v[8:11], v[160:163], 0
	v_mfma_f32_16x16x32_bf16 v[40:43], v[0:3], v[168:171], 0
	v_mfma_f32_16x16x32_bf16 v[44:47], v[8:11], v[168:171], 0
	v_mfma_f32_16x16x32_bf16 v[48:51], v[0:3], v[176:179], 0
	v_mfma_f32_16x16x32_bf16 v[52:55], v[8:11], v[176:179], 0
	v_mfma_f32_16x16x32_bf16 v[24:27], v[4:7], v[156:159], v[24:27]
	v_mfma_f32_16x16x32_bf16 v[28:31], v[12:15], v[156:159], v[28:31]
	v_mfma_f32_16x16x32_bf16 v[32:35], v[4:7], v[164:167], v[32:35]
	v_mfma_f32_16x16x32_bf16 v[36:39], v[12:15], v[164:167], v[36:39]
	v_mfma_f32_16x16x32_bf16 v[40:43], v[4:7], v[172:175], v[40:43]
	v_mfma_f32_16x16x32_bf16 v[44:47], v[12:15], v[172:175], v[44:47]
	v_mfma_f32_16x16x32_bf16 v[48:51], v[4:7], v[180:183], v[48:51]
	v_mfma_f32_16x16x32_bf16 v[52:55], v[12:15], v[180:183], v[52:55]
	v_mfma_f32_16x16x32_bf16 v[56:59], v[196:199], v[152:155], 0
	v_mfma_f32_16x16x32_bf16 v[60:63], v[204:207], v[152:155], 0
	v_mfma_f32_16x16x32_bf16 v[64:67], v[196:199], v[160:163], 0
	v_mfma_f32_16x16x32_bf16 v[68:71], v[204:207], v[160:163], 0
	v_mfma_f32_16x16x32_bf16 v[72:75], v[196:199], v[168:171], 0
	v_mfma_f32_16x16x32_bf16 v[76:79], v[204:207], v[168:171], 0
	v_mfma_f32_16x16x32_bf16 v[80:83], v[196:199], v[176:179], 0
	v_mfma_f32_16x16x32_bf16 v[84:87], v[204:207], v[176:179], 0
	v_mfma_f32_16x16x32_bf16 v[56:59], v[200:203], v[156:159], v[56:59]
	v_mfma_f32_16x16x32_bf16 v[60:63], v[208:211], v[156:159], v[60:63]
	v_mfma_f32_16x16x32_bf16 v[64:67], v[200:203], v[164:167], v[64:67]
	v_mfma_f32_16x16x32_bf16 v[68:71], v[208:211], v[164:167], v[68:71]
	v_mfma_f32_16x16x32_bf16 v[72:75], v[200:203], v[172:175], v[72:75]
	v_mfma_f32_16x16x32_bf16 v[76:79], v[208:211], v[172:175], v[76:79]
	v_mfma_f32_16x16x32_bf16 v[80:83], v[200:203], v[180:183], v[80:83]
	v_mfma_f32_16x16x32_bf16 v[84:87], v[208:211], v[180:183], v[84:87]
	s_setprio 0
	s_barrier
	ds_read_b128 v[152:155], v186 offset:16400
	ds_read_b128 v[156:159], v187 offset:16400
	ds_read_b128 v[160:163], v186 offset:18448
	ds_read_b128 v[164:167], v187 offset:18448
	ds_read_b128 v[168:171], v186 offset:20496
	ds_read_b128 v[172:175], v187 offset:20496
	ds_read_b128 v[176:179], v186 offset:22544
	ds_read_b128 v[180:183], v187 offset:22544
	s_cmp_lg_u32 s0, s54
	s_cbranch_scc1 .Lgu_nosw1
	s_mov_b64 s[66:67], s[74:75]
	s_mov_b64 s[70:71], s[80:81]
	s_mov_b64 s[72:73], s[82:83]
.Lgu_nosw1:
	s_add_i32 m0, s39, 0x10000
	s_nop 0
	global_load_lds_dwordx4 v184, s[70:71]
	s_add_i32 m0, s39, 0x10400
	s_nop 0
	global_load_lds_dwordx4 v185, s[70:71]
	s_add_u32 s70, s70, 0x80
	s_addc_u32 s71, s71, 0
	s_add_i32 m0, s39, 0x0
	s_nop 0
	global_load_lds_dwordx4 v184, s[66:67]
	s_add_i32 m0, s39, 0x400
	s_nop 0
	global_load_lds_dwordx4 v185, s[66:67]
	s_add_u32 s66, s66, 0x80
	s_addc_u32 s67, s67, 0
	s_add_i32 m0, s39, 0x14000
	s_nop 0
	global_load_lds_dwordx4 v184, s[72:73]
	s_add_i32 m0, s39, 0x14400
	s_nop 0
	global_load_lds_dwordx4 v185, s[72:73]
	s_add_u32 s72, s72, 0x80
	s_addc_u32 s73, s73, 0
	s_waitcnt lgkmcnt(0)
	s_waitcnt vmcnt(8)
	s_barrier
	s_setprio 1
	v_mfma_f32_16x16x32_bf16 v[88:91], v[0:3], v[152:155], 0
	v_mfma_f32_16x16x32_bf16 v[92:95], v[8:11], v[152:155], 0
	v_mfma_f32_16x16x32_bf16 v[96:99], v[0:3], v[160:163], 0
	v_mfma_f32_16x16x32_bf16 v[100:103], v[8:11], v[160:163], 0
	v_mfma_f32_16x16x32_bf16 v[104:107], v[0:3], v[168:171], 0
	v_mfma_f32_16x16x32_bf16 v[108:111], v[8:11], v[168:171], 0
	v_mfma_f32_16x16x32_bf16 v[112:115], v[0:3], v[176:179], 0
	v_mfma_f32_16x16x32_bf16 v[116:119], v[8:11], v[176:179], 0
	v_mfma_f32_16x16x32_bf16 v[88:91], v[4:7], v[156:159], v[88:91]
	v_mfma_f32_16x16x32_bf16 v[92:95], v[12:15], v[156:159], v[92:95]
	v_mfma_f32_16x16x32_bf16 v[96:99], v[4:7], v[164:167], v[96:99]
	v_mfma_f32_16x16x32_bf16 v[100:103], v[12:15], v[164:167], v[100:103]
	v_mfma_f32_16x16x32_bf16 v[104:107], v[4:7], v[172:175], v[104:107]
	v_mfma_f32_16x16x32_bf16 v[108:111], v[12:15], v[172:175], v[108:111]
	v_mfma_f32_16x16x32_bf16 v[112:115], v[4:7], v[180:183], v[112:115]
	v_mfma_f32_16x16x32_bf16 v[116:119], v[12:15], v[180:183], v[116:119]
	v_mfma_f32_16x16x32_bf16 v[120:123], v[196:199], v[152:155], 0
	v_mfma_f32_16x16x32_bf16 v[124:127], v[204:207], v[152:155], 0
	v_mfma_f32_16x16x32_bf16 v[128:131], v[196:199], v[160:163], 0
	v_mfma_f32_16x16x32_bf16 v[132:135], v[204:207], v[160:163], 0
	v_mfma_f32_16x16x32_bf16 v[136:139], v[196:199], v[168:171], 0
	v_mfma_f32_16x16x32_bf16 v[140:143], v[204:207], v[168:171], 0
	v_mfma_f32_16x16x32_bf16 v[144:147], v[196:199], v[176:179], 0
	v_mfma_f32_16x16x32_bf16 v[148:151], v[204:207], v[176:179], 0
	v_mfma_f32_16x16x32_bf16 v[120:123], v[200:203], v[156:159], v[120:123]
	v_mfma_f32_16x16x32_bf16 v[124:127], v[208:211], v[156:159], v[124:127]
	v_mfma_f32_16x16x32_bf16 v[128:131], v[200:203], v[164:167], v[128:131]
	v_mfma_f32_16x16x32_bf16 v[132:135], v[208:211], v[164:167], v[132:135]
	v_mfma_f32_16x16x32_bf16 v[136:139], v[200:203], v[172:175], v[136:139]
	v_mfma_f32_16x16x32_bf16 v[140:143], v[208:211], v[172:175], v[140:143]
	v_mfma_f32_16x16x32_bf16 v[144:147], v[200:203], v[180:183], v[144:147]
	v_mfma_f32_16x16x32_bf16 v[148:151], v[208:211], v[180:183], v[148:151]
	s_setprio 0
	s_barrier
; #define LAS __attribute__((address_space(3)))
; #define BAR() { __builtin_amdgcn_sched_barrier(0); __builtin_amdgcn_s_barrier(); asm volatile("" ::: "memory"); __builtin_amdgcn_sched_barrier(0); }
; DI void gemm_stream2(const bf16_t* __restrict__ A, int lda, const bf16_t* __restrict__ Bt, int ldb, int K, int m0, int n0, ...
;     ...
;     for (int kt = 0; kt < nk; ++kt) {
;         const bool pf = (kt + 2 < nk) || has_next, more = (kt + 1 < nk) || has_next;
;         const bf16_t* pa = (kt + 2 < nk) ? ga + (kt + 2) * 64 : gan + (kt + 2 - nk) * 64;
;         const bf16_t* pb = (kt + 2 < nk) ? gb + (kt + 2) * 64 : gbn + (kt + 2 - nk) * 64;
;         const int plda = (kt + 2 < nk) ? lda : ldan, pldb = (kt + 2 < nk) ? ldb : ldbn;
;         const int s2 = st >= 1 ? st - 1 : 2;
;         const LAS char* base = lds + st * 49152;
; #pragma unroll
;         for (int ks = 0; ks < 2; ++ks) {
;             const unsigned fo = ks ? fo1 : fo0;
;             bf16x8 af[4], bfr[4];
; #pragma unroll
;             for (int i = 0; i < 4; ++i) { af[i] = *(const LAS bf16x8*)(base + aoff + i * 2048 + fo); bfr[i] = *(const LAS bf16x8*)(base + boff + i * 2048 + fo); }
;             if (ks == 1 && more) { if (pf) asm volatile("s_waitcnt vmcnt(3)" ::: "memory"); else asm volatile("s_waitcnt vmcnt(0)" ::: "memory"); }
;             if (pf) { PIECE(s2, ks * 3 + 0); PIECE(s2, ks * 3 + 1); PIECE(s2, ks * 3 + 2); }
;             asm volatile("s_waitcnt lgkmcnt(0)" ::: "memory");
;             BAR();
;             __builtin_amdgcn_s_setprio(1);
; #pragma unroll
;             for (int mi = 0; mi < 4; ++mi)
; #pragma unroll
;                 for (int ni = 0; ni < 4; ++ni) acc[mi][ni] = __builtin_amdgcn_mfma_f32_16x16x32_bf16(bfr[ni], af[mi], acc[mi][ni], 0, 0, 0);
;             __builtin_amdgcn_s_setprio(0);
;             BAR();
;         }
;         st = st == 2 ? 0 : st + 1;
;     }
	ds_read_b128 v[0:3], v188 offset:32784
	ds_read_b128 v[4:7], v189 offset:32784
	ds_read_b128 v[8:11], v188 offset:34832
	ds_read_b128 v[12:15], v189 offset:34832
	ds_read_b128 v[196:199], v188 offset:49168
	ds_read_b128 v[200:203], v189 offset:49168
	ds_read_b128 v[204:207], v188 offset:51216
	ds_read_b128 v[208:211], v189 offset:51216
	ds_read_b128 v[152:155], v186 offset:32784
	ds_read_b128 v[156:159], v187 offset:32784
	ds_read_b128 v[160:163], v186 offset:34832
	ds_read_b128 v[164:167], v187 offset:34832
	ds_read_b128 v[168:171], v186 offset:36880
	ds_read_b128 v[172:175], v187 offset:36880
	ds_read_b128 v[176:179], v186 offset:38928
	ds_read_b128 v[180:183], v187 offset:38928
	s_cmp_lg_u32 s0, s54
	s_cbranch_scc1 .Lgu_nosw2
	s_mov_b64 s[68:69], s[78:79]
.Lgu_nosw2:
	s_add_i32 m0, s39, 0x4000
	s_nop 0
	global_load_lds_dwordx4 v184, s[68:69]
	s_add_i32 m0, s39, 0x4400
	s_nop 0
	global_load_lds_dwordx4 v185, s[68:69]
	s_add_u32 s68, s68, 0x80
	s_addc_u32 s69, s69, 0
	s_waitcnt lgkmcnt(0)
	s_waitcnt vmcnt(8)
	s_barrier
	s_setprio 1
	v_mfma_f32_16x16x32_bf16 v[24:27], v[0:3], v[152:155], v[24:27]
	v_mfma_f32_16x16x32_bf16 v[28:31], v[8:11], v[152:155], v[28:31]
	v_mfma_f32_16x16x32_bf16 v[32:35], v[0:3], v[160:163], v[32:35]
	v_mfma_f32_16x16x32_bf16 v[36:39], v[8:11], v[160:163], v[36:39]
	v_mfma_f32_16x16x32_bf16 v[40:43], v[0:3], v[168:171], v[40:43]
	v_mfma_f32_16x16x32_bf16 v[44:47], v[8:11], v[168:171], v[44:47]
	v_mfma_f32_16x16x32_bf16 v[48:51], v[0:3], v[176:179], v[48:51]
	v_mfma_f32_16x16x32_bf16 v[52:55], v[8:11], v[176:179], v[52:55]
	v_mfma_f32_16x16x32_bf16 v[24:27], v[4:7], v[156:159], v[24:27]
	v_mfma_f32_16x16x32_bf16 v[28:31], v[12:15], v[156:159], v[28:31]
	v_mfma_f32_16x16x32_bf16 v[32:35], v[4:7], v[164:167], v[32:35]
	v_mfma_f32_16x16x32_bf16 v[36:39], v[12:15], v[164:167], v[36:39]
	v_mfma_f32_16x16x32_bf16 v[40:43], v[4:7], v[172:175], v[40:43]
	v_mfma_f32_16x16x32_bf16 v[44:47], v[12:15], v[172:175], v[44:47]
	v_mfma_f32_16x16x32_bf16 v[48:51], v[4:7], v[180:183], v[48:51]
	v_mfma_f32_16x16x32_bf16 v[52:55], v[12:15], v[180:183], v[52:55]
	v_mfma_f32_16x16x32_bf16 v[56:59], v[196:199], v[152:155], v[56:59]
	v_mfma_f32_16x16x32_bf16 v[60:63], v[204:207], v[152:155], v[60:63]
	v_mfma_f32_16x16x32_bf16 v[64:67], v[196:199], v[160:163], v[64:67]
	v_mfma_f32_16x16x32_bf16 v[68:71], v[204:207], v[160:163], v[68:71]
	v_mfma_f32_16x16x32_bf16 v[72:75], v[196:199], v[168:171], v[72:75]
	v_mfma_f32_16x16x32_bf16 v[76:79], v[204:207], v[168:171], v[76:79]
	v_mfma_f32_16x16x32_bf16 v[80:83], v[196:199], v[176:179], v[80:83]
	v_mfma_f32_16x16x32_bf16 v[84:87], v[204:207], v[176:179], v[84:87]
	v_mfma_f32_16x16x32_bf16 v[56:59], v[200:203], v[156:159], v[56:59]
	v_mfma_f32_16x16x32_bf16 v[60:63], v[208:211], v[156:159], v[60:63]
	v_mfma_f32_16x16x32_bf16 v[64:67], v[200:203], v[164:167], v[64:67]
	v_mfma_f32_16x16x32_bf16 v[68:71], v[208:211], v[164:167], v[68:71]
	v_mfma_f32_16x16x32_bf16 v[72:75], v[200:203], v[172:175], v[72:75]
	v_mfma_f32_16x16x32_bf16 v[76:79], v[208:211], v[172:175], v[76:79]
	v_mfma_f32_16x16x32_bf16 v[80:83], v[200:203], v[180:183], v[80:83]
	v_mfma_f32_16x16x32_bf16 v[84:87], v[208:211], v[180:183], v[84:87]
	s_setprio 0
	s_barrier
	ds_read_b128 v[152:155], v186 offset:49168
	ds_read_b128 v[156:159], v187 offset:49168
	ds_read_b128 v[160:163], v186 offset:51216
	ds_read_b128 v[164:167], v187 offset:51216
	ds_read_b128 v[168:171], v186 offset:53264
	ds_read_b128 v[172:175], v187 offset:53264
	ds_read_b128 v[176:179], v186 offset:55312
	ds_read_b128 v[180:183], v187 offset:55312
	s_add_i32 m0, s39, 0x18000
	s_nop 0
	global_load_lds_dwordx4 v184, s[70:71]
	s_add_i32 m0, s39, 0x18400
	s_nop 0
	global_load_lds_dwordx4 v185, s[70:71]
	s_add_u32 s70, s70, 0x80
	s_addc_u32 s71, s71, 0
	s_add_i32 m0, s39, 0x8000
	s_nop 0
	global_load_lds_dwordx4 v184, s[66:67]
	s_add_i32 m0, s39, 0x8400
	s_nop 0
	global_load_lds_dwordx4 v185, s[66:67]
	s_add_u32 s66, s66, 0x80
	s_addc_u32 s67, s67, 0
	s_add_i32 m0, s39, 0x1c000
	s_nop 0
	global_load_lds_dwordx4 v184, s[72:73]
	s_add_i32 m0, s39, 0x1c400
	s_nop 0
	global_load_lds_dwordx4 v185, s[72:73]
	s_add_u32 s72, s72, 0x80
	s_addc_u32 s73, s73, 0
	s_waitcnt lgkmcnt(0)
	s_waitcnt vmcnt(8)
	s_barrier
	s_setprio 1
	v_mfma_f32_16x16x32_bf16 v[88:91], v[0:3], v[152:155], v[88:91]
	v_mfma_f32_16x16x32_bf16 v[92:95], v[8:11], v[152:155], v[92:95]
	v_mfma_f32_16x16x32_bf16 v[96:99], v[0:3], v[160:163], v[96:99]
	v_mfma_f32_16x16x32_bf16 v[100:103], v[8:11], v[160:163], v[100:103]
	v_mfma_f32_16x16x32_bf16 v[104:107], v[0:3], v[168:171], v[104:107]
	v_mfma_f32_16x16x32_bf16 v[108:111], v[8:11], v[168:171], v[108:111]
	v_mfma_f32_16x16x32_bf16 v[112:115], v[0:3], v[176:179], v[112:115]
	v_mfma_f32_16x16x32_bf16 v[116:119], v[8:11], v[176:179], v[116:119]
	v_mfma_f32_16x16x32_bf16 v[88:91], v[4:7], v[156:159], v[88:91]
	v_mfma_f32_16x16x32_bf16 v[92:95], v[12:15], v[156:159], v[92:95]
	v_mfma_f32_16x16x32_bf16 v[96:99], v[4:7], v[164:167], v[96:99]
	v_mfma_f32_16x16x32_bf16 v[100:103], v[12:15], v[164:167], v[100:103]
	v_mfma_f32_16x16x32_bf16 v[104:107], v[4:7], v[172:175], v[104:107]
	v_mfma_f32_16x16x32_bf16 v[108:111], v[12:15], v[172:175], v[108:111]
	v_mfma_f32_16x16x32_bf16 v[112:115], v[4:7], v[180:183], v[112:115]
	v_mfma_f32_16x16x32_bf16 v[116:119], v[12:15], v[180:183], v[116:119]
	v_mfma_f32_16x16x32_bf16 v[120:123], v[196:199], v[152:155], v[120:123]
	v_mfma_f32_16x16x32_bf16 v[124:127], v[204:207], v[152:155], v[124:127]
	v_mfma_f32_16x16x32_bf16 v[128:131], v[196:199], v[160:163], v[128:131]
	v_mfma_f32_16x16x32_bf16 v[132:135], v[204:207], v[160:163], v[132:135]
	v_mfma_f32_16x16x32_bf16 v[136:139], v[196:199], v[168:171], v[136:139]
	v_mfma_f32_16x16x32_bf16 v[140:143], v[204:207], v[168:171], v[140:143]
	v_mfma_f32_16x16x32_bf16 v[144:147], v[196:199], v[176:179], v[144:147]
	v_mfma_f32_16x16x32_bf16 v[148:151], v[204:207], v[176:179], v[148:151]
	v_mfma_f32_16x16x32_bf16 v[120:123], v[200:203], v[156:159], v[120:123]
	v_mfma_f32_16x16x32_bf16 v[124:127], v[208:211], v[156:159], v[124:127]
	v_mfma_f32_16x16x32_bf16 v[128:131], v[200:203], v[164:167], v[128:131]
	v_mfma_f32_16x16x32_bf16 v[132:135], v[208:211], v[164:167], v[132:135]
	v_mfma_f32_16x16x32_bf16 v[136:139], v[200:203], v[172:175], v[136:139]
	v_mfma_f32_16x16x32_bf16 v[140:143], v[208:211], v[172:175], v[140:143]
	v_mfma_f32_16x16x32_bf16 v[144:147], v[200:203], v[180:183], v[144:147]
	v_mfma_f32_16x16x32_bf16 v[148:151], v[208:211], v[180:183], v[148:151]
	s_setprio 0
	s_barrier
	s_sub_u32 s0, s0, 1
; #define LAS __attribute__((address_space(3)))
; #define BAR() { __builtin_amdgcn_sched_barrier(0); __builtin_amdgcn_s_barrier(); asm volatile("" ::: "memory"); __builtin_amdgcn_sched_barrier(0); }
; DI void gemm_stream2(const bf16_t* __restrict__ A, int lda, const bf16_t* __restrict__ Bt, int ldb, int K, int m0, int n0, ...
;     ...
;     for (int kt = 0; kt < nk; ++kt) {
;         const bool pf = (kt + 2 < nk) || has_next, more = (kt + 1 < nk) || has_next;
;         const bf16_t* pa = (kt + 2 < nk) ? ga + (kt + 2) * 64 : gan + (kt + 2 - nk) * 64;
;         const bf16_t* pb = (kt + 2 < nk) ? gb + (kt + 2) * 64 : gbn + (kt + 2 - nk) * 64;
;         const int plda = (kt + 2 < nk) ? lda : ldan, pldb = (kt + 2 < nk) ? ldb : ldbn;
;         const int s2 = st >= 1 ? st - 1 : 2;
;         const LAS char* base = lds + st * 49152;
; #pragma unroll
;         for (int ks = 0; ks < 2; ++ks) {
;             const unsigned fo = ks ? fo1 : fo0;
;             bf16x8 af[4], bfr[4];
; #pragma unroll
;             for (int i = 0; i < 4; ++i) { af[i] = *(const LAS bf16x8*)(base + aoff + i * 2048 + fo); bfr[i] = *(const LAS bf16x8*)(base + boff + i * 2048 + fo); }
;             if (ks == 1 && more) { if (pf) asm volatile("s_waitcnt vmcnt(3)" ::: "memory"); else asm volatile("s_waitcnt vmcnt(0)" ::: "memory"); }
;             if (pf) { PIECE(s2, ks * 3 + 0); PIECE(s2, ks * 3 + 1); PIECE(s2, ks * 3 + 2); }
;             asm volatile("s_waitcnt lgkmcnt(0)" ::: "memory");
;             BAR();
;             __builtin_amdgcn_s_setprio(1);
; #pragma unroll
;             for (int mi = 0; mi < 4; ++mi)
; #pragma unroll
;                 for (int ni = 0; ni < 4; ++ni) acc[mi][ni] = __builtin_amdgcn_mfma_f32_16x16x32_bf16(bfr[ni], af[mi], acc[mi][ni], 0, 0, 0);
;             __builtin_amdgcn_s_setprio(0);
;             BAR();
;         }
.Lgu_kloop:
	ds_read_b128 v[0:3], v188 offset:16
	ds_read_b128 v[4:7], v189 offset:16
	ds_read_b128 v[8:11], v188 offset:2064
	ds_read_b128 v[12:15], v189 offset:2064
	ds_read_b128 v[196:199], v188 offset:16400
	ds_read_b128 v[200:203], v189 offset:16400
	ds_read_b128 v[204:207], v188 offset:18448
	ds_read_b128 v[208:211], v189 offset:18448
	ds_read_b128 v[152:155], v186 offset:16
	ds_read_b128 v[156:159], v187 offset:16
	ds_read_b128 v[160:163], v186 offset:2064
	ds_read_b128 v[164:167], v187 offset:2064
	ds_read_b128 v[168:171], v186 offset:4112
	ds_read_b128 v[172:175], v187 offset:4112
	ds_read_b128 v[176:179], v186 offset:6160
	ds_read_b128 v[180:183], v187 offset:6160
	s_add_i32 m0, s39, 0xc000
	s_nop 0
	global_load_lds_dwordx4 v184, s[68:69]
	s_add_i32 m0, s39, 0xc400
	s_nop 0
	global_load_lds_dwordx4 v185, s[68:69]
	s_add_u32 s68, s68, 0x80
	s_addc_u32 s69, s69, 0
	s_waitcnt lgkmcnt(0)
	s_waitcnt vmcnt(8)
	s_barrier
	s_setprio 1
	v_mfma_f32_16x16x32_bf16 v[24:27], v[0:3], v[152:155], v[24:27]
	v_mfma_f32_16x16x32_bf16 v[28:31], v[8:11], v[152:155], v[28:31]
	v_mfma_f32_16x16x32_bf16 v[32:35], v[0:3], v[160:163], v[32:35]
	v_mfma_f32_16x16x32_bf16 v[36:39], v[8:11], v[160:163], v[36:39]
	v_mfma_f32_16x16x32_bf16 v[40:43], v[0:3], v[168:171], v[40:43]
	v_mfma_f32_16x16x32_bf16 v[44:47], v[8:11], v[168:171], v[44:47]
	v_mfma_f32_16x16x32_bf16 v[48:51], v[0:3], v[176:179], v[48:51]
	v_mfma_f32_16x16x32_bf16 v[52:55], v[8:11], v[176:179], v[52:55]
	v_mfma_f32_16x16x32_bf16 v[24:27], v[4:7], v[156:159], v[24:27]
	v_mfma_f32_16x16x32_bf16 v[28:31], v[12:15], v[156:159], v[28:31]
	v_mfma_f32_16x16x32_bf16 v[32:35], v[4:7], v[164:167], v[32:35]
	v_mfma_f32_16x16x32_bf16 v[36:39], v[12:15], v[164:167], v[36:39]
	v_mfma_f32_16x16x32_bf16 v[40:43], v[4:7], v[172:175], v[40:43]
	v_mfma_f32_16x16x32_bf16 v[44:47], v[12:15], v[172:175], v[44:47]
	v_mfma_f32_16x16x32_bf16 v[48:51], v[4:7], v[180:183], v[48:51]
	v_mfma_f32_16x16x32_bf16 v[52:55], v[12:15], v[180:183], v[52:55]
	v_mfma_f32_16x16x32_bf16 v[56:59], v[196:199], v[152:155], v[56:59]
	v_mfma_f32_16x16x32_bf16 v[60:63], v[204:207], v[152:155], v[60:63]
	v_mfma_f32_16x16x32_bf16 v[64:67], v[196:199], v[160:163], v[64:67]
	v_mfma_f32_16x16x32_bf16 v[68:71], v[204:207], v[160:163], v[68:71]
	v_mfma_f32_16x16x32_bf16 v[72:75], v[196:199], v[168:171], v[72:75]
	v_mfma_f32_16x16x32_bf16 v[76:79], v[204:207], v[168:171], v[76:79]
	v_mfma_f32_16x16x32_bf16 v[80:83], v[196:199], v[176:179], v[80:83]
	v_mfma_f32_16x16x32_bf16 v[84:87], v[204:207], v[176:179], v[84:87]
	v_mfma_f32_16x16x32_bf16 v[56:59], v[200:203], v[156:159], v[56:59]
	v_mfma_f32_16x16x32_bf16 v[60:63], v[208:211], v[156:159], v[60:63]
	v_mfma_f32_16x16x32_bf16 v[64:67], v[200:203], v[164:167], v[64:67]
	v_mfma_f32_16x16x32_bf16 v[68:71], v[208:211], v[164:167], v[68:71]
	v_mfma_f32_16x16x32_bf16 v[72:75], v[200:203], v[172:175], v[72:75]
	v_mfma_f32_16x16x32_bf16 v[76:79], v[208:211], v[172:175], v[76:79]
	v_mfma_f32_16x16x32_bf16 v[80:83], v[200:203], v[180:183], v[80:83]
	v_mfma_f32_16x16x32_bf16 v[84:87], v[208:211], v[180:183], v[84:87]
	s_setprio 0
	s_barrier
	ds_read_b128 v[152:155], v186 offset:16400
	ds_read_b128 v[156:159], v187 offset:16400
	ds_read_b128 v[160:163], v186 offset:18448
	ds_read_b128 v[164:167], v187 offset:18448
	ds_read_b128 v[168:171], v186 offset:20496
	ds_read_b128 v[172:175], v187 offset:20496
	ds_read_b128 v[176:179], v186 offset:22544
	ds_read_b128 v[180:183], v187 offset:22544
	s_cmp_lg_u32 s0, s54
	s_cbranch_scc1 .Lgu_nosw3
	s_mov_b64 s[66:67], s[74:75]
	s_mov_b64 s[70:71], s[80:81]
	s_mov_b64 s[72:73], s[82:83]

; #define LAS __attribute__((address_space(3)))
; #define BAR() { __builtin_amdgcn_sched_barrier(0); __builtin_amdgcn_s_barrier(); asm volatile("" ::: "memory"); __builtin_amdgcn_sched_barrier(0); }
; DI void gemm_stream2(const bf16_t* __restrict__ A, int lda, const bf16_t* __restrict__ Bt, int ldb, int K, int m0, int n0, ...
;     ...
;     for (int kt = 0; kt < nk; ++kt) {
;         const bool pf = (kt + 2 < nk) || has_next, more = (kt + 1 < nk) || has_next;
;         const bf16_t* pa = (kt + 2 < nk) ? ga + (kt + 2) * 64 : gan + (kt + 2 - nk) * 64;
;         const bf16_t* pb = (kt + 2 < nk) ? gb + (kt + 2) * 64 : gbn + (kt + 2 - nk) * 64;
;         const int plda = (kt + 2 < nk) ? lda : ldan, pldb = (kt + 2 < nk) ? ldb : ldbn;
;         const int s2 = st >= 1 ? st - 1 : 2;
;         const LAS char* base = lds + st * 49152;
; #pragma unroll
;         for (int ks = 0; ks < 2; ++ks) {
;             const unsigned fo = ks ? fo1 : fo0;
;             bf16x8 af[4], bfr[4];
; #pragma unroll
;             for (int i = 0; i < 4; ++i) { af[i] = *(const LAS bf16x8*)(base + aoff + i * 2048 + fo); bfr[i] = *(const LAS bf16x8*)(base + boff + i * 2048 + fo); }
;             if (ks == 1 && more) { if (pf) asm volatile("s_waitcnt vmcnt(3)" ::: "memory"); else asm volatile("s_waitcnt vmcnt(0)" ::: "memory"); }
;             if (pf) { PIECE(s2, ks * 3 + 0); PIECE(s2, ks * 3 + 1); PIECE(s2, ks * 3 + 2); }
;             asm volatile("s_waitcnt lgkmcnt(0)" ::: "memory");
;             BAR();
;             __builtin_amdgcn_s_setprio(1);
; #pragma unroll
;             for (int mi = 0; mi < 4; ++mi)
; #pragma unroll
;                 for (int ni = 0; ni < 4; ++ni) acc[mi][ni] = __builtin_amdgcn_mfma_f32_16x16x32_bf16(bfr[ni], af[mi], acc[mi][ni], 0, 0, 0);
;             __builtin_amdgcn_s_setprio(0);
;             BAR();
;         }
;         st = st == 2 ? 0 : st + 1;
;     }
.Lin_nosw2:
	s_add_i32 m0, s39, 0x4000
	s_nop 0
	global_load_lds_dwordx4 v184, s[68:69]
	s_add_i32 m0, s39, 0x4400
	s_nop 0
	global_load_lds_dwordx4 v185, s[68:69]
	s_add_u32 s68, s68, 0x80
	s_addc_u32 s69, s69, 0
	s_waitcnt lgkmcnt(0)
	s_waitcnt vmcnt(8)
	s_barrier
	s_setprio 1
	v_mfma_f32_16x16x32_bf16 v[24:27], v[0:3], v[152:155], v[24:27]
	v_mfma_f32_16x16x32_bf16 v[28:31], v[8:11], v[152:155], v[28:31]
	v_mfma_f32_16x16x32_bf16 v[32:35], v[0:3], v[160:163], v[32:35]
	v_mfma_f32_16x16x32_bf16 v[36:39], v[8:11], v[160:163], v[36:39]
	v_mfma_f32_16x16x32_bf16 v[40:43], v[0:3], v[168:171], v[40:43]
	v_mfma_f32_16x16x32_bf16 v[44:47], v[8:11], v[168:171], v[44:47]
	v_mfma_f32_16x16x32_bf16 v[48:51], v[0:3], v[176:179], v[48:51]
	v_mfma_f32_16x16x32_bf16 v[52:55], v[8:11], v[176:179], v[52:55]
	v_mfma_f32_16x16x32_bf16 v[24:27], v[4:7], v[156:159], v[24:27]
	v_mfma_f32_16x16x32_bf16 v[28:31], v[12:15], v[156:159], v[28:31]
	v_mfma_f32_16x16x32_bf16 v[32:35], v[4:7], v[164:167], v[32:35]
	v_mfma_f32_16x16x32_bf16 v[36:39], v[12:15], v[164:167], v[36:39]
	v_mfma_f32_16x16x32_bf16 v[40:43], v[4:7], v[172:175], v[40:43]
	v_mfma_f32_16x16x32_bf16 v[44:47], v[12:15], v[172:175], v[44:47]
	v_mfma_f32_16x16x32_bf16 v[48:51], v[4:7], v[180:183], v[48:51]
	v_mfma_f32_16x16x32_bf16 v[52:55], v[12:15], v[180:183], v[52:55]
	v_mfma_f32_16x16x32_bf16 v[56:59], v[196:199], v[152:155], v[56:59]
	v_mfma_f32_16x16x32_bf16 v[60:63], v[204:207], v[152:155], v[60:63]
	v_mfma_f32_16x16x32_bf16 v[64:67], v[196:199], v[160:163], v[64:67]
	v_mfma_f32_16x16x32_bf16 v[68:71], v[204:207], v[160:163], v[68:71]
	v_mfma_f32_16x16x32_bf16 v[72:75], v[196:199], v[168:171], v[72:75]
	v_mfma_f32_16x16x32_bf16 v[76:79], v[204:207], v[168:171], v[76:79]
	v_mfma_f32_16x16x32_bf16 v[80:83], v[196:199], v[176:179], v[80:83]
	v_mfma_f32_16x16x32_bf16 v[84:87], v[204:207], v[176:179], v[84:87]
	v_mfma_f32_16x16x32_bf16 v[56:59], v[200:203], v[156:159], v[56:59]
	v_mfma_f32_16x16x32_bf16 v[60:63], v[208:211], v[156:159], v[60:63]
	v_mfma_f32_16x16x32_bf16 v[64:67], v[200:203], v[164:167], v[64:67]
	v_mfma_f32_16x16x32_bf16 v[68:71], v[208:211], v[164:167], v[68:71]
	v_mfma_f32_16x16x32_bf16 v[72:75], v[200:203], v[172:175], v[72:75]
	v_mfma_f32_16x16x32_bf16 v[76:79], v[208:211], v[172:175], v[76:79]
	v_mfma_f32_16x16x32_bf16 v[80:83], v[200:203], v[180:183], v[80:83]
	v_mfma_f32_16x16x32_bf16 v[84:87], v[208:211], v[180:183], v[84:87]
	s_setprio 0
	s_barrier
	ds_read_b128 v[152:155], v186 offset:49168
	ds_read_b128 v[156:159], v187 offset:49168
	ds_read_b128 v[160:163], v186 offset:51216
	ds_read_b128 v[164:167], v187 offset:51216
	ds_read_b128 v[168:171], v186 offset:53264
	ds_read_b128 v[172:175], v187 offset:53264
	ds_read_b128 v[176:179], v186 offset:55312
	ds_read_b128 v[180:183], v187 offset:55312
	s_add_i32 m0, s39, 0x18000
	s_nop 0
	global_load_lds_dwordx4 v184, s[70:71]
	s_add_i32 m0, s39, 0x18400
	s_nop 0
	global_load_lds_dwordx4 v185, s[70:71]
	s_add_u32 s70, s70, 0x80
	s_addc_u32 s71, s71, 0
	s_add_i32 m0, s39, 0x8000
	s_nop 0
	global_load_lds_dwordx4 v184, s[66:67]
	s_add_i32 m0, s39, 0x8400
	s_nop 0
	global_load_lds_dwordx4 v185, s[66:67]
	s_add_u32 s66, s66, 0x80
	s_addc_u32 s67, s67, 0
	s_add_i32 m0, s39, 0x1c000
	s_nop 0
	global_load_lds_dwordx4 v184, s[72:73]
	s_add_i32 m0, s39, 0x1c400
	s_nop 0
	global_load_lds_dwordx4 v185, s[72:73]
	s_add_u32 s72, s72, 0x80
	s_addc_u32 s73, s73, 0
	s_waitcnt lgkmcnt(0)
	s_waitcnt vmcnt(8)
	s_barrier
	s_setprio 1
	v_mfma_f32_16x16x32_bf16 v[88:91], v[0:3], v[152:155], v[88:91]
	v_mfma_f32_16x16x32_bf16 v[92:95], v[8:11], v[152:155], v[92:95]
	v_mfma_f32_16x16x32_bf16 v[96:99], v[0:3], v[160:163], v[96:99]
	v_mfma_f32_16x16x32_bf16 v[100:103], v[8:11], v[160:163], v[100:103]
	v_mfma_f32_16x16x32_bf16 v[104:107], v[0:3], v[168:171], v[104:107]
	v_mfma_f32_16x16x32_bf16 v[108:111], v[8:11], v[168:171], v[108:111]
	v_mfma_f32_16x16x32_bf16 v[112:115], v[0:3], v[176:179], v[112:115]
	v_mfma_f32_16x16x32_bf16 v[116:119], v[8:11], v[176:179], v[116:119]
	v_mfma_f32_16x16x32_bf16 v[88:91], v[4:7], v[156:159], v[88:91]
	v_mfma_f32_16x16x32_bf16 v[92:95], v[12:15], v[156:159], v[92:95]
	v_mfma_f32_16x16x32_bf16 v[96:99], v[4:7], v[164:167], v[96:99]
	v_mfma_f32_16x16x32_bf16 v[100:103], v[12:15], v[164:167], v[100:103]
	v_mfma_f32_16x16x32_bf16 v[104:107], v[4:7], v[172:175], v[104:107]
	v_mfma_f32_16x16x32_bf16 v[108:111], v[12:15], v[172:175], v[108:111]
	v_mfma_f32_16x16x32_bf16 v[112:115], v[4:7], v[180:183], v[112:115]
	v_mfma_f32_16x16x32_bf16 v[116:119], v[12:15], v[180:183], v[116:119]
	v_mfma_f32_16x16x32_bf16 v[120:123], v[196:199], v[152:155], v[120:123]
	v_mfma_f32_16x16x32_bf16 v[124:127], v[204:207], v[152:155], v[124:127]
	v_mfma_f32_16x16x32_bf16 v[128:131], v[196:199], v[160:163], v[128:131]
	v_mfma_f32_16x16x32_bf16 v[132:135], v[204:207], v[160:163], v[132:135]
	v_mfma_f32_16x16x32_bf16 v[136:139], v[196:199], v[168:171], v[136:139]
	v_mfma_f32_16x16x32_bf16 v[140:143], v[204:207], v[168:171], v[140:143]
	v_mfma_f32_16x16x32_bf16 v[144:147], v[196:199], v[176:179], v[144:147]
	v_mfma_f32_16x16x32_bf16 v[148:151], v[204:207], v[176:179], v[148:151]
	v_mfma_f32_16x16x32_bf16 v[120:123], v[200:203], v[156:159], v[120:123]
	v_mfma_f32_16x16x32_bf16 v[124:127], v[208:211], v[156:159], v[124:127]
	v_mfma_f32_16x16x32_bf16 v[128:131], v[200:203], v[164:167], v[128:131]
	v_mfma_f32_16x16x32_bf16 v[132:135], v[208:211], v[164:167], v[132:135]
	v_mfma_f32_16x16x32_bf16 v[136:139], v[200:203], v[172:175], v[136:139]
	v_mfma_f32_16x16x32_bf16 v[140:143], v[208:211], v[172:175], v[140:143]
	v_mfma_f32_16x16x32_bf16 v[144:147], v[200:203], v[180:183], v[144:147]
	v_mfma_f32_16x16x32_bf16 v[148:151], v[208:211], v[180:183], v[148:151]
	s_setprio 0
	s_barrier
	s_sub_u32 s0, s0, 1
; #define LAS __attribute__((address_space(3)))
; #define BAR() { __builtin_amdgcn_sched_barrier(0); __builtin_amdgcn_s_barrier(); asm volatile("" ::: "memory"); __builtin_amdgcn_sched_barrier(0); }
; DI void gemm_stream2(const bf16_t* __restrict__ A, int lda, const bf16_t* __restrict__ Bt, int ldb, int K, int m0, int n0, ...
;     ...
;     for (int kt = 0; kt < nk; ++kt) {
;         const bool pf = (kt + 2 < nk) || has_next, more = (kt + 1 < nk) || has_next;
;         const bf16_t* pa = (kt + 2 < nk) ? ga + (kt + 2) * 64 : gan + (kt + 2 - nk) * 64;
;         const bf16_t* pb = (kt + 2 < nk) ? gb + (kt + 2) * 64 : gbn + (kt + 2 - nk) * 64;
;         const int plda = (kt + 2 < nk) ? lda : ldan, pldb = (kt + 2 < nk) ? ldb : ldbn;
;         const int s2 = st >= 1 ? st - 1 : 2;
;         const LAS char* base = lds + st * 49152;
; #pragma unroll
;         for (int ks = 0; ks < 2; ++ks) {
;             const unsigned fo = ks ? fo1 : fo0;
;             bf16x8 af[4], bfr[4];
; #pragma unroll
;             for (int i = 0; i < 4; ++i) { af[i] = *(const LAS bf16x8*)(base + aoff + i * 2048 + fo); bfr[i] = *(const LAS bf16x8*)(base + boff + i * 2048 + fo); }
;             if (ks == 1 && more) { if (pf) asm volatile("s_waitcnt vmcnt(3)" ::: "memory"); else asm volatile("s_waitcnt vmcnt(0)" ::: "memory"); }
;             if (pf) { PIECE(s2, ks * 3 + 0); PIECE(s2, ks * 3 + 1); PIECE(s2, ks * 3 + 2); }
;             asm volatile("s_waitcnt lgkmcnt(0)" ::: "memory");
;             BAR();
;             __builtin_amdgcn_s_setprio(1);
; #pragma unroll
;             for (int mi = 0; mi < 4; ++mi)
; #pragma unroll
;                 for (int ni = 0; ni < 4; ++ni) acc[mi][ni] = __builtin_amdgcn_mfma_f32_16x16x32_bf16(bfr[ni], af[mi], acc[mi][ni], 0, 0, 0);
;             __builtin_amdgcn_s_setprio(0);
;             BAR();
;         }
.Lin_kloop:
	ds_read_b128 v[0:3], v188 offset:16
	ds_read_b128 v[4:7], v189 offset:16
	ds_read_b128 v[8:11], v188 offset:2064
	ds_read_b128 v[12:15], v189 offset:2064
	ds_read_b128 v[196:199], v188 offset:16400
	ds_read_b128 v[200:203], v189 offset:16400
	ds_read_b128 v[204:207], v188 offset:18448
	ds_read_b128 v[208:211], v189 offset:18448
	ds_read_b128 v[152:155], v186 offset:16
	ds_read_b128 v[156:159], v187 offset:16
	ds_read_b128 v[160:163], v186 offset:2064
	ds_read_b128 v[164:167], v187 offset:2064
	ds_read_b128 v[168:171], v186 offset:4112
	ds_read_b128 v[172:175], v187 offset:4112
	ds_read_b128 v[176:179], v186 offset:6160
	ds_read_b128 v[180:183], v187 offset:6160
	s_add_i32 m0, s39, 0xc000
	s_nop 0
	global_load_lds_dwordx4 v184, s[68:69]
	s_add_i32 m0, s39, 0xc400
	s_nop 0
	global_load_lds_dwordx4 v185, s[68:69]
	s_add_u32 s68, s68, 0x80
	s_addc_u32 s69, s69, 0
	s_waitcnt lgkmcnt(0)
	s_waitcnt vmcnt(8)
	s_barrier
	s_setprio 1
	v_mfma_f32_16x16x32_bf16 v[24:27], v[0:3], v[152:155], v[24:27]
	v_mfma_f32_16x16x32_bf16 v[28:31], v[8:11], v[152:155], v[28:31]
	v_mfma_f32_16x16x32_bf16 v[32:35], v[0:3], v[160:163], v[32:35]
	v_mfma_f32_16x16x32_bf16 v[36:39], v[8:11], v[160:163], v[36:39]
	v_mfma_f32_16x16x32_bf16 v[40:43], v[0:3], v[168:171], v[40:43]
	v_mfma_f32_16x16x32_bf16 v[44:47], v[8:11], v[168:171], v[44:47]
	v_mfma_f32_16x16x32_bf16 v[48:51], v[0:3], v[176:179], v[48:51]
	v_mfma_f32_16x16x32_bf16 v[52:55], v[8:11], v[176:179], v[52:55]
	v_mfma_f32_16x16x32_bf16 v[24:27], v[4:7], v[156:159], v[24:27]
	v_mfma_f32_16x16x32_bf16 v[28:31], v[12:15], v[156:159], v[28:31]
	v_mfma_f32_16x16x32_bf16 v[32:35], v[4:7], v[164:167], v[32:35]
	v_mfma_f32_16x16x32_bf16 v[36:39], v[12:15], v[164:167], v[36:39]
	v_mfma_f32_16x16x32_bf16 v[40:43], v[4:7], v[172:175], v[40:43]
	v_mfma_f32_16x16x32_bf16 v[44:47], v[12:15], v[172:175], v[44:47]
	v_mfma_f32_16x16x32_bf16 v[48:51], v[4:7], v[180:183], v[48:51]
	v_mfma_f32_16x16x32_bf16 v[52:55], v[12:15], v[180:183], v[52:55]
	v_mfma_f32_16x16x32_bf16 v[56:59], v[196:199], v[152:155], v[56:59]
	v_mfma_f32_16x16x32_bf16 v[60:63], v[204:207], v[152:155], v[60:63]
	v_mfma_f32_16x16x32_bf16 v[64:67], v[196:199], v[160:163], v[64:67]
	v_mfma_f32_16x16x32_bf16 v[68:71], v[204:207], v[160:163], v[68:71]
	v_mfma_f32_16x16x32_bf16 v[72:75], v[196:199], v[168:171], v[72:75]
	v_mfma_f32_16x16x32_bf16 v[76:79], v[204:207], v[168:171], v[76:79]
	v_mfma_f32_16x16x32_bf16 v[80:83], v[196:199], v[176:179], v[80:83]
	v_mfma_f32_16x16x32_bf16 v[84:87], v[204:207], v[176:179], v[84:87]
	v_mfma_f32_16x16x32_bf16 v[56:59], v[200:203], v[156:159], v[56:59]
	v_mfma_f32_16x16x32_bf16 v[60:63], v[208:211], v[156:159], v[60:63]
	v_mfma_f32_16x16x32_bf16 v[64:67], v[200:203], v[164:167], v[64:67]
	v_mfma_f32_16x16x32_bf16 v[68:71], v[208:211], v[164:167], v[68:71]
	v_mfma_f32_16x16x32_bf16 v[72:75], v[200:203], v[172:175], v[72:75]
	v_mfma_f32_16x16x32_bf16 v[76:79], v[208:211], v[172:175], v[76:79]
	v_mfma_f32_16x16x32_bf16 v[80:83], v[200:203], v[180:183], v[80:83]
	v_mfma_f32_16x16x32_bf16 v[84:87], v[208:211], v[180:183], v[84:87]
	s_setprio 0
	s_barrier
	ds_read_b128 v[152:155], v186 offset:16400
	ds_read_b128 v[156:159], v187 offset:16400
	ds_read_b128 v[160:163], v186 offset:18448
	ds_read_b128 v[164:167], v187 offset:18448
	ds_read_b128 v[168:171], v186 offset:20496
	ds_read_b128 v[172:175], v187 offset:20496
	ds_read_b128 v[176:179], v186 offset:22544
	ds_read_b128 v[180:183], v187 offset:22544
	s_cmp_lg_u32 s0, s54
	s_cbranch_scc1 .Lin_nosw3
	s_mov_b64 s[66:67], s[74:75]
	s_mov_b64 s[70:71], s[80:81]
	s_mov_b64 s[72:73], s[82:83]
